# in-projection GEMM phase: no per-segment priority flips, static priority 1 for waves 0-3
# baseline (speedup 1.0000x reference)
; #define LAS __attribute__((address_space(3)))
; __device__ __forceinline__ int opaque_tid() { int t; asm volatile("v_mov_b32 %0, %1" : "=v"(t) : "v"((int)threadIdx.x)); return t; }
;     __device__ __forceinline__ bool next(int i, Unit& u) const {
;         const int ti = i / rep; u.z = i - ti * rep;
;         const long L = (long)ti * G + c; const int n1 = nM1 * nN1, n2 = nM2 * nN2;
;         if (L >= n1 + n2) return false;
;         if (L < n1) rect_order((int)L, nM1, nN1, u.pm, u.pn);
;         else { const int r = (int)L - n1; u.pm = nM1 + r / nN2; u.pn = r % nN2; }
;         return true;
;     }
; template <class Epi>
; __device__ __forceinline__ void gemm_phase(LAS unsigned char* lds, const Gemm g, const Sched& S, const Epi& E) {
;     const int tid = opaque_tid(), wid = __builtin_amdgcn_readfirstlane(tid >> 6), lane = tid & 63, wr = wid >> 2, wc = wid & 3, fr = lane & 15, fq = lane >> 4;
.LBB0_280:
	v_readfirstlane_b32 s1, v194
	s_nop 0
	s_bitcmp1_b32 s1, 8
	s_cbranch_scc1 .Lmy_bp
	s_setprio 1
.Lmy_bp:
	s_nop 0
	s_nop 0
	s_nop 0
	s_nop 0
	s_nop 0
	s_nop 0
	s_nop 0
	s_nop 0
	s_nop 0
	s_nop 0
	v_writelane_b32 v250, s6, 25
	v_readlane_b32 s1, v253, 24
	s_mov_b64 s[24:25], s[72:73]
	v_writelane_b32 v250, s7, 26
	v_readlane_b32 s6, v254, 62
	v_readlane_b32 s7, v254, 63
	s_mov_b32 s38, s1
	v_readlane_b32 s1, v253, 23
	v_mov_b32 v14, v194
	s_and_b64 vcc, exec, s[6:7]
	v_readfirstlane_b32 s26, v14
	s_mov_b32 s54, s1
	s_cbranch_vccz .LBB0_282
	v_readlane_b32 s1, v250, 5
	s_mov_b32 s38, s1
	v_readlane_b32 s1, v250, 3
	s_mov_b32 s54, s1

; #define PG8_STAGE(bufoff, gbase, voff) do { _Pragma("unroll") for (int _i = 0; _i < 2; ++_i) \
;         __builtin_amdgcn_global_load_lds((const unsigned*)((const char*)(gbase) + (voff)[_i]), (LAS unsigned*)(lds + (bufoff) + ldsw + _i * 8192), 16, 0, 0); } while (0)
; #define PG8_LDA(dst, b, h) do { _Pragma("unroll") for (int m = 0; m < 4; ++m) _Pragma("unroll") for (int k = 0; k < 2; ++k) dst[m][k] = *(const LAS bf16x8*)(lds + PG8_SA(b, h) + aoff + m * 2048 + k * 1024); } while (0)
; #define PG8_LDB(dst, b, h) do { _Pragma("unroll") for (int n = 0; n < 2; ++n) _Pragma("unroll") for (int k = 0; k < 2; ++k) dst[n][k] = *(const LAS bf16x8*)(lds + PG8_SB(b, h) + boff + n * 2048 + k * 1024); } while (0)
; #define PG8_MMA(ai, bj, At, Bt) do { __builtin_amdgcn_s_setprio(1); _Pragma("unroll") for (int m = 0; m < 4; ++m) _Pragma("unroll") for (int n = 0; n < 2; ++n) _Pragma("unroll") for (int k = 0; k < 2; ++k) \
;         acc[ai][bj][m][n] = __builtin_amdgcn_mfma_f32_16x16x32_bf16(Bt[n][k], At[m][k], acc[ai][bj][m][n], 0, 0, 0); __builtin_amdgcn_s_setprio(0); } while (0)
; #define PG8_WAIT_V(n) asm volatile("s_waitcnt vmcnt(" #n ")" ::: "memory")
; #define PG8_WAIT_L(n) asm volatile("s_waitcnt lgkmcnt(" #n ")" ::: "memory")
; #define PG8_BAR __builtin_amdgcn_s_barrier()
; #define PG8_SCHED __builtin_amdgcn_sched_barrier(0)
; template <class Epi>
; __device__ __forceinline__ void gemm_phase(LAS unsigned char* lds, const Gemm g, const Sched& S, const Epi& E) {
;     ...
;         for (int t = 0; t < nt; t += 2) {
;             const bool last = (t == nt - 2);
;             const char* a1 = cA + (size_t)(t + 1) * kstep;
;             const char* a2 = last ? nA : cA + (size_t)(t + 2) * kstep; const char* b2 = last ? nB : cB + (size_t)(t + 2) * kstep;
;             const char* a3 = a2 + kstep; const char* b3 = b2 + kstep;
;             PG8_LDB(B0, 0, 0); PG8_LDB(B1, 0, 1); PG8_SCHED; PG8_LDA(At, 0, 0); PG8_STAGE(PG8_SA(1, 1), a1 + hstep, voffA);
;             PG8_WAIT_V(8); PG8_WAIT_L(0); PG8_BAR; PG8_MMA(0, 0, At, B0); PG8_MMA(0, 1, At, B1); PG8_BAR; PG8_SCHED;
;             PG8_LDA(At, 0, 1); PG8_STAGE(PG8_SB(0, 0), b2, voffB); PG8_STAGE(PG8_SB(0, 1), b2 + hstep, voffB); PG8_STAGE(PG8_SA(0, 0), a2, voffA);
;             PG8_WAIT_V(8); PG8_WAIT_L(0); PG8_BAR; PG8_MMA(1, 0, At, B0); PG8_MMA(1, 1, At, B1); PG8_BAR; PG8_SCHED;
.LBB0_294:
	s_add_u32 s14, s56, 0xfffc0080
	s_addc_u32 s15, s57, -1
	s_add_i32 s55, 0, 0x10000
	s_cmp_eq_u32 s49, 12
	s_cselect_b32 s23, s24, s15
	s_cselect_b32 s22, s25, s14
	v_add_u32_e32 v148, s55, v157
	s_cselect_b32 s21, s26, s47
	s_cselect_b32 s20, s27, s39
	s_add_i32 s14, 0, 0x14000
	ds_read_b128 v[144:147], v148
	ds_read_b128 v[160:163], v148 offset:1024
	ds_read_b128 v[164:167], v148 offset:2048
	ds_read_b128 v[168:171], v148 offset:3072
	v_add_u32_e32 v148, s14, v157
	ds_read_b128 v[172:175], v148
	ds_read_b128 v[176:179], v148 offset:1024
	ds_read_b128 v[180:183], v148 offset:2048
	ds_read_b128 v[184:187], v148 offset:3072
	v_lshl_add_u64 v[148:149], s[56:57], 0, v[142:143]
	s_add_i32 m0, s28, 0xc000
	ds_read_b128 v[188:191], v159
	ds_read_b128 v[214:217], v159 offset:1024
	ds_read_b128 v[218:221], v159 offset:2048
	ds_read_b128 v[222:225], v159 offset:3072
	ds_read_b128 v[226:229], v159 offset:4096
	ds_read_b128 v[230:233], v159 offset:5120
	ds_read_b128 v[234:237], v159 offset:6144
	ds_read_b128 v[238:241], v159 offset:7168
	global_load_lds_dwordx4 v[148:149], off
	v_lshl_add_u64 v[148:149], s[56:57], 0, v[140:141]
	s_add_i32 m0, s28, 0xe000
	s_nop 0
	global_load_lds_dwordx4 v[148:149], off
	s_waitcnt vmcnt(8)
	s_waitcnt lgkmcnt(0)
	s_barrier
	s_nop 0
	s_waitcnt lgkmcnt(0)
	v_mfma_f32_16x16x32_bf16 v[130:133], v[144:147], v[188:191], v[130:133]
	v_mfma_f32_16x16x32_bf16 v[126:129], v[164:167], v[188:191], v[126:129]
	v_mfma_f32_16x16x32_bf16 v[114:117], v[144:147], v[218:221], v[114:117]
	v_mfma_f32_16x16x32_bf16 v[110:113], v[164:167], v[218:221], v[110:113]
	v_mfma_f32_16x16x32_bf16 v[98:101], v[144:147], v[226:229], v[98:101]
	v_mfma_f32_16x16x32_bf16 v[94:97], v[164:167], v[226:229], v[94:97]
	v_mfma_f32_16x16x32_bf16 v[82:85], v[144:147], v[234:237], v[82:85]
	v_mfma_f32_16x16x32_bf16 v[78:81], v[164:167], v[234:237], v[78:81]
	v_mfma_f32_16x16x32_bf16 v[130:133], v[160:163], v[214:217], v[130:133]
	v_mfma_f32_16x16x32_bf16 v[126:129], v[168:171], v[214:217], v[126:129]
	v_mfma_f32_16x16x32_bf16 v[114:117], v[160:163], v[222:225], v[114:117]
	v_mfma_f32_16x16x32_bf16 v[110:113], v[168:171], v[222:225], v[110:113]
	v_mfma_f32_16x16x32_bf16 v[98:101], v[160:163], v[230:233], v[98:101]
	v_mfma_f32_16x16x32_bf16 v[94:97], v[168:171], v[230:233], v[94:97]
	v_mfma_f32_16x16x32_bf16 v[82:85], v[160:163], v[238:241], v[82:85]
	v_mfma_f32_16x16x32_bf16 v[78:81], v[168:171], v[238:241], v[78:81]
	s_nop 0
	s_nop 0
	v_mfma_f32_16x16x32_bf16 v[122:125], v[172:175], v[188:191], v[122:125]
	v_mfma_f32_16x16x32_bf16 v[118:121], v[180:183], v[188:191], v[118:121]
	v_mfma_f32_16x16x32_bf16 v[106:109], v[172:175], v[218:221], v[106:109]
	v_mfma_f32_16x16x32_bf16 v[102:105], v[180:183], v[218:221], v[102:105]
	v_mfma_f32_16x16x32_bf16 v[90:93], v[172:175], v[226:229], v[90:93]
	v_mfma_f32_16x16x32_bf16 v[86:89], v[180:183], v[226:229], v[86:89]
	v_mfma_f32_16x16x32_bf16 v[74:77], v[172:175], v[234:237], v[74:77]
	v_mfma_f32_16x16x32_bf16 v[70:73], v[180:183], v[234:237], v[70:73]
	v_mfma_f32_16x16x32_bf16 v[122:125], v[176:179], v[214:217], v[122:125]
	v_mfma_f32_16x16x32_bf16 v[118:121], v[184:187], v[214:217], v[118:121]
	v_mfma_f32_16x16x32_bf16 v[106:109], v[176:179], v[222:225], v[106:109]
	v_mfma_f32_16x16x32_bf16 v[102:105], v[184:187], v[222:225], v[102:105]
	v_mfma_f32_16x16x32_bf16 v[90:93], v[176:179], v[230:233], v[90:93]
	v_mfma_f32_16x16x32_bf16 v[86:89], v[184:187], v[230:233], v[86:89]
	v_mfma_f32_16x16x32_bf16 v[74:77], v[176:179], v[238:241], v[74:77]
	v_mfma_f32_16x16x32_bf16 v[70:73], v[184:187], v[238:241], v[70:73]
	s_nop 0
	s_barrier
	s_add_i32 s15, s55, s19
	v_lshl_add_u64 v[148:149], s[20:21], 0, v[0:1]
	s_mov_b32 m0, s15
	ds_read_b128 v[188:191], v159 offset:16384
	ds_read_b128 v[214:217], v159 offset:17408
	ds_read_b128 v[218:221], v159 offset:18432
	ds_read_b128 v[222:225], v159 offset:19456
	ds_read_b128 v[226:229], v159 offset:20480
	ds_read_b128 v[230:233], v159 offset:21504
	ds_read_b128 v[234:237], v159 offset:22528
	ds_read_b128 v[238:241], v159 offset:23552
	global_load_lds_dwordx4 v[148:149], off
	s_add_i32 m0, s15, 0x2000
	s_add_u32 s58, s20, 0x40000
	v_lshl_add_u64 v[192:193], s[20:21], 0, v[138:139]
	s_addc_u32 s59, s21, 0
	s_add_i32 s14, s14, s19
	global_load_lds_dwordx4 v[192:193], off
	v_lshl_add_u64 v[242:243], s[58:59], 0, v[0:1]
	s_mov_b32 m0, s14
	v_lshl_add_u64 v[244:245], s[22:23], 0, v[136:137]
	global_load_lds_dwordx4 v[242:243], off
	v_lshl_add_u64 v[242:243], s[58:59], 0, v[138:139]
	s_add_i32 m0, s14, 0x2000
	s_nop 0
	global_load_lds_dwordx4 v[242:243], off
	v_lshl_add_u64 v[242:243], s[22:23], 0, v[134:135]
	s_mov_b32 m0, s28
	s_nop 0
	global_load_lds_dwordx4 v[242:243], off
	s_mov_b32 m0, s29
	s_nop 0
	global_load_lds_dwordx4 v[244:245], off
	s_waitcnt vmcnt(8)
	s_waitcnt lgkmcnt(0)
	s_barrier
; #define PG8_STAGE(bufoff, gbase, voff) do { _Pragma("unroll") for (int _i = 0; _i < 2; ++_i) \
;         __builtin_amdgcn_global_load_lds((const unsigned*)((const char*)(gbase) + (voff)[_i]), (LAS unsigned*)(lds + (bufoff) + ldsw + _i * 8192), 16, 0, 0); } while (0)
; #define PG8_LDA(dst, b, h) do { _Pragma("unroll") for (int m = 0; m < 4; ++m) _Pragma("unroll") for (int k = 0; k < 2; ++k) dst[m][k] = *(const LAS bf16x8*)(lds + PG8_SA(b, h) + aoff + m * 2048 + k * 1024); } while (0)
; #define PG8_LDB(dst, b, h) do { _Pragma("unroll") for (int n = 0; n < 2; ++n) _Pragma("unroll") for (int k = 0; k < 2; ++k) dst[n][k] = *(const LAS bf16x8*)(lds + PG8_SB(b, h) + boff + n * 2048 + k * 1024); } while (0)
; #define PG8_MMA(ai, bj, At, Bt) do { __builtin_amdgcn_s_setprio(1); _Pragma("unroll") for (int m = 0; m < 4; ++m) _Pragma("unroll") for (int n = 0; n < 2; ++n) _Pragma("unroll") for (int k = 0; k < 2; ++k) \
;         acc[ai][bj][m][n] = __builtin_amdgcn_mfma_f32_16x16x32_bf16(Bt[n][k], At[m][k], acc[ai][bj][m][n], 0, 0, 0); __builtin_amdgcn_s_setprio(0); } while (0)
; #define PG8_WAIT_V(n) asm volatile("s_waitcnt vmcnt(" #n ")" ::: "memory")
; #define PG8_WAIT_L(n) asm volatile("s_waitcnt lgkmcnt(" #n ")" ::: "memory")
; #define PG8_BAR __builtin_amdgcn_s_barrier()
; #define PG8_SCHED __builtin_amdgcn_sched_barrier(0)
; template <class Epi>
; __device__ __forceinline__ void gemm_phase(LAS unsigned char* lds, const Gemm g, const Sched& S, const Epi& E) {
;     ...
;             PG8_LDA(At, 0, 1); PG8_STAGE(PG8_SB(0, 0), b2, voffB); PG8_STAGE(PG8_SB(0, 1), b2 + hstep, voffB); PG8_STAGE(PG8_SA(0, 0), a2, voffA);
;             PG8_WAIT_V(8); PG8_WAIT_L(0); PG8_BAR; PG8_MMA(1, 0, At, B0); PG8_MMA(1, 1, At, B1); PG8_BAR; PG8_SCHED;
;             PG8_LDB(B0, 1, 0); PG8_LDB(B1, 1, 1); PG8_SCHED; PG8_LDA(At, 1, 0); PG8_STAGE(PG8_SA(0, 1), a2 + hstep, voffA);
;             PG8_WAIT_V(8); PG8_WAIT_L(0); PG8_BAR; PG8_MMA(0, 0, At, B0); PG8_MMA(0, 1, At, B1); PG8_BAR; PG8_SCHED;
	s_nop 0
	s_waitcnt lgkmcnt(0)
	v_mfma_f32_16x16x32_bf16 v[66:69], v[144:147], v[188:191], v[66:69]
	v_mfma_f32_16x16x32_bf16 v[62:65], v[164:167], v[188:191], v[62:65]
	v_mfma_f32_16x16x32_bf16 v[50:53], v[144:147], v[218:221], v[50:53]
	v_mfma_f32_16x16x32_bf16 v[46:49], v[164:167], v[218:221], v[46:49]
	v_mfma_f32_16x16x32_bf16 v[34:37], v[144:147], v[226:229], v[34:37]
	v_mfma_f32_16x16x32_bf16 v[30:33], v[164:167], v[226:229], v[30:33]
	v_mfma_f32_16x16x32_bf16 v[18:21], v[144:147], v[234:237], v[18:21]
	v_mfma_f32_16x16x32_bf16 v[14:17], v[164:167], v[234:237], v[14:17]
	v_mfma_f32_16x16x32_bf16 v[66:69], v[160:163], v[214:217], v[66:69]
	v_mfma_f32_16x16x32_bf16 v[62:65], v[168:171], v[214:217], v[62:65]
	v_mfma_f32_16x16x32_bf16 v[50:53], v[160:163], v[222:225], v[50:53]
	v_mfma_f32_16x16x32_bf16 v[46:49], v[168:171], v[222:225], v[46:49]
	v_mfma_f32_16x16x32_bf16 v[34:37], v[160:163], v[230:233], v[34:37]
	v_mfma_f32_16x16x32_bf16 v[30:33], v[168:171], v[230:233], v[30:33]
	v_mfma_f32_16x16x32_bf16 v[18:21], v[160:163], v[238:241], v[18:21]
	v_mfma_f32_16x16x32_bf16 v[14:17], v[168:171], v[238:241], v[14:17]
	s_nop 0
	s_nop 0
	v_mfma_f32_16x16x32_bf16 v[58:61], v[172:175], v[188:191], v[58:61]
	v_mfma_f32_16x16x32_bf16 v[54:57], v[180:183], v[188:191], v[54:57]
	v_mfma_f32_16x16x32_bf16 v[42:45], v[172:175], v[218:221], v[42:45]
	v_mfma_f32_16x16x32_bf16 v[38:41], v[180:183], v[218:221], v[38:41]
	v_mfma_f32_16x16x32_bf16 v[26:29], v[172:175], v[226:229], v[26:29]
	v_mfma_f32_16x16x32_bf16 v[22:25], v[180:183], v[226:229], v[22:25]
	v_mfma_f32_16x16x32_bf16 v[6:9], v[172:175], v[234:237], v[6:9]
	v_mfma_f32_16x16x32_bf16 v[2:5], v[180:183], v[234:237], v[2:5]
	v_mfma_f32_16x16x32_bf16 v[58:61], v[176:179], v[214:217], v[58:61]
	v_mfma_f32_16x16x32_bf16 v[54:57], v[184:187], v[214:217], v[54:57]
	v_mfma_f32_16x16x32_bf16 v[42:45], v[176:179], v[222:225], v[42:45]
	v_mfma_f32_16x16x32_bf16 v[38:41], v[184:187], v[222:225], v[38:41]
	v_mfma_f32_16x16x32_bf16 v[26:29], v[176:179], v[230:233], v[26:29]
	v_mfma_f32_16x16x32_bf16 v[22:25], v[184:187], v[230:233], v[22:25]
	v_mfma_f32_16x16x32_bf16 v[6:9], v[176:179], v[238:241], v[6:9]
	v_mfma_f32_16x16x32_bf16 v[2:5], v[184:187], v[238:241], v[2:5]
	s_nop 0
	s_barrier
	s_add_i32 s14, 0, 0x18000
	s_add_i32 s15, 0, 0x1c000
	v_add_u32_e32 v168, s14, v157
	v_add_u32_e32 v184, s15, v157
	ds_read_b128 v[144:147], v168
	ds_read_b128 v[160:163], v168 offset:1024
	ds_read_b128 v[164:167], v168 offset:2048
	ds_read_b128 v[168:171], v168 offset:3072
	ds_read_b128 v[172:175], v184
	ds_read_b128 v[176:179], v184 offset:1024
	ds_read_b128 v[180:183], v184 offset:2048
	ds_read_b128 v[184:187], v184 offset:3072
	s_add_u32 s22, s22, 0x40000
	s_addc_u32 s23, s23, 0
	s_mov_b32 m0, s30
	v_lshl_add_u64 v[246:247], s[22:23], 0, v[134:135]
	ds_read_b128 v[188:191], v159 offset:32768
	ds_read_b128 v[214:217], v159 offset:33792
	ds_read_b128 v[218:221], v159 offset:34816
	ds_read_b128 v[222:225], v159 offset:35840
	ds_read_b128 v[226:229], v159 offset:36864
	ds_read_b128 v[230:233], v159 offset:37888
	ds_read_b128 v[234:237], v159 offset:38912
	ds_read_b128 v[238:241], v159 offset:39936
	global_load_lds_dwordx4 v[246:247], off
	v_lshl_add_u64 v[246:247], s[22:23], 0, v[136:137]
	s_mov_b32 m0, s31
	s_nop 0
	global_load_lds_dwordx4 v[246:247], off
	s_waitcnt vmcnt(8)
	s_waitcnt lgkmcnt(0)
	s_barrier
	s_nop 0
	s_waitcnt lgkmcnt(0)
	v_mfma_f32_16x16x32_bf16 v[130:133], v[144:147], v[188:191], v[130:133]
	v_mfma_f32_16x16x32_bf16 v[126:129], v[164:167], v[188:191], v[126:129]
	v_mfma_f32_16x16x32_bf16 v[114:117], v[144:147], v[218:221], v[114:117]
	v_mfma_f32_16x16x32_bf16 v[110:113], v[164:167], v[218:221], v[110:113]
	v_mfma_f32_16x16x32_bf16 v[98:101], v[144:147], v[226:229], v[98:101]
	v_mfma_f32_16x16x32_bf16 v[94:97], v[164:167], v[226:229], v[94:97]
	v_mfma_f32_16x16x32_bf16 v[82:85], v[144:147], v[234:237], v[82:85]
	v_mfma_f32_16x16x32_bf16 v[78:81], v[164:167], v[234:237], v[78:81]
	v_mfma_f32_16x16x32_bf16 v[130:133], v[160:163], v[214:217], v[130:133]
	v_mfma_f32_16x16x32_bf16 v[126:129], v[168:171], v[214:217], v[126:129]
	v_mfma_f32_16x16x32_bf16 v[114:117], v[160:163], v[222:225], v[114:117]
	v_mfma_f32_16x16x32_bf16 v[110:113], v[168:171], v[222:225], v[110:113]
	v_mfma_f32_16x16x32_bf16 v[98:101], v[160:163], v[230:233], v[98:101]
	v_mfma_f32_16x16x32_bf16 v[94:97], v[168:171], v[230:233], v[94:97]
	v_mfma_f32_16x16x32_bf16 v[82:85], v[160:163], v[238:241], v[82:85]
	v_mfma_f32_16x16x32_bf16 v[78:81], v[168:171], v[238:241], v[78:81]
	s_nop 0
	s_nop 0
	v_mfma_f32_16x16x32_bf16 v[122:125], v[172:175], v[188:191], v[122:125]
	v_mfma_f32_16x16x32_bf16 v[118:121], v[180:183], v[188:191], v[118:121]
	v_mfma_f32_16x16x32_bf16 v[106:109], v[172:175], v[218:221], v[106:109]
	v_mfma_f32_16x16x32_bf16 v[102:105], v[180:183], v[218:221], v[102:105]
	v_mfma_f32_16x16x32_bf16 v[90:93], v[172:175], v[226:229], v[90:93]
	v_mfma_f32_16x16x32_bf16 v[86:89], v[180:183], v[226:229], v[86:89]
	v_mfma_f32_16x16x32_bf16 v[74:77], v[172:175], v[234:237], v[74:77]
	v_mfma_f32_16x16x32_bf16 v[70:73], v[180:183], v[234:237], v[70:73]
	v_mfma_f32_16x16x32_bf16 v[122:125], v[176:179], v[214:217], v[122:125]
	v_mfma_f32_16x16x32_bf16 v[118:121], v[184:187], v[214:217], v[118:121]
	v_mfma_f32_16x16x32_bf16 v[106:109], v[176:179], v[222:225], v[106:109]
	v_mfma_f32_16x16x32_bf16 v[102:105], v[184:187], v[222:225], v[102:105]
	v_mfma_f32_16x16x32_bf16 v[90:93], v[176:179], v[230:233], v[90:93]
	v_mfma_f32_16x16x32_bf16 v[86:89], v[184:187], v[230:233], v[86:89]
	v_mfma_f32_16x16x32_bf16 v[74:77], v[176:179], v[238:241], v[74:77]
	v_mfma_f32_16x16x32_bf16 v[70:73], v[184:187], v[238:241], v[70:73]
	s_nop 0
	s_barrier
; #define PG8_STAGE(bufoff, gbase, voff) do { _Pragma("unroll") for (int _i = 0; _i < 2; ++_i) \
;         __builtin_amdgcn_global_load_lds((const unsigned*)((const char*)(gbase) + (voff)[_i]), (LAS unsigned*)(lds + (bufoff) + ldsw + _i * 8192), 16, 0, 0); } while (0)
; #define PG8_LDA(dst, b, h) do { _Pragma("unroll") for (int m = 0; m < 4; ++m) _Pragma("unroll") for (int k = 0; k < 2; ++k) dst[m][k] = *(const LAS bf16x8*)(lds + PG8_SA(b, h) + aoff + m * 2048 + k * 1024); } while (0)
; #define PG8_LDB(dst, b, h) do { _Pragma("unroll") for (int n = 0; n < 2; ++n) _Pragma("unroll") for (int k = 0; k < 2; ++k) dst[n][k] = *(const LAS bf16x8*)(lds + PG8_SB(b, h) + boff + n * 2048 + k * 1024); } while (0)
; #define PG8_MMA(ai, bj, At, Bt) do { __builtin_amdgcn_s_setprio(1); _Pragma("unroll") for (int m = 0; m < 4; ++m) _Pragma("unroll") for (int n = 0; n < 2; ++n) _Pragma("unroll") for (int k = 0; k < 2; ++k) \
;         acc[ai][bj][m][n] = __builtin_amdgcn_mfma_f32_16x16x32_bf16(Bt[n][k], At[m][k], acc[ai][bj][m][n], 0, 0, 0); __builtin_amdgcn_s_setprio(0); } while (0)
; #define PG8_WAIT_V(n) asm volatile("s_waitcnt vmcnt(" #n ")" ::: "memory")
; #define PG8_WAIT_L(n) asm volatile("s_waitcnt lgkmcnt(" #n ")" ::: "memory")
; #define PG8_BAR __builtin_amdgcn_s_barrier()
; #define PG8_SCHED __builtin_amdgcn_sched_barrier(0)
; template <class Epi>
; __device__ __forceinline__ void gemm_phase(LAS unsigned char* lds, const Gemm g, const Sched& S, const Epi& E) {
;     ...
;             PG8_LDB(B0, 1, 0); PG8_LDB(B1, 1, 1); PG8_SCHED; PG8_LDA(At, 1, 0); PG8_STAGE(PG8_SA(0, 1), a2 + hstep, voffA);
;             PG8_WAIT_V(8); PG8_WAIT_L(0); PG8_BAR; PG8_MMA(0, 0, At, B0); PG8_MMA(0, 1, At, B1); PG8_BAR; PG8_SCHED;
;             PG8_LDA(At, 1, 1); PG8_STAGE(PG8_SB(1, 0), b3, voffB); PG8_STAGE(PG8_SB(1, 1), b3 + hstep, voffB); PG8_STAGE(PG8_SA(1, 0), a3, voffA);
;             PG8_WAIT_V(8); PG8_WAIT_L(0); PG8_BAR; PG8_MMA(1, 0, At, B0); PG8_MMA(1, 1, At, B1); PG8_BAR; PG8_SCHED;
;         }
;         if (wr == 0) PG8_BAR;
	s_add_i32 s14, s14, s19
	v_lshl_add_u64 v[148:149], v[148:149], 0, s[86:87]
	s_mov_b32 m0, s14
	ds_read_b128 v[188:191], v159 offset:49152
	ds_read_b128 v[214:217], v159 offset:50176
	ds_read_b128 v[218:221], v159 offset:51200
	ds_read_b128 v[222:225], v159 offset:52224
	ds_read_b128 v[226:229], v159 offset:53248
	ds_read_b128 v[230:233], v159 offset:54272
	ds_read_b128 v[234:237], v159 offset:55296
	ds_read_b128 v[238:241], v159 offset:56320
	global_load_lds_dwordx4 v[148:149], off
	s_add_i32 m0, s14, 0x2000
	s_add_u32 s20, s20, 0x40080
	v_lshl_add_u64 v[148:149], v[192:193], 0, s[86:87]
	s_addc_u32 s21, s21, 0
	s_add_i32 s14, s15, s19
	global_load_lds_dwordx4 v[148:149], off
	v_lshl_add_u64 v[148:149], s[20:21], 0, v[0:1]
	s_mov_b32 m0, s14
	s_nop 0
	global_load_lds_dwordx4 v[148:149], off
	v_lshl_add_u64 v[148:149], s[20:21], 0, v[138:139]
	s_add_i32 m0, s14, 0x2000
	s_nop 0
	global_load_lds_dwordx4 v[148:149], off
	v_lshl_add_u64 v[148:149], v[242:243], 0, s[86:87]
	s_mov_b32 m0, s33
	s_nop 0
	global_load_lds_dwordx4 v[148:149], off
	v_lshl_add_u64 v[148:149], v[244:245], 0, s[86:87]
	s_mov_b32 m0, s34
	s_nop 0
	global_load_lds_dwordx4 v[148:149], off
	s_waitcnt vmcnt(8)
	s_waitcnt lgkmcnt(0)
	s_barrier
	s_nop 0
	s_waitcnt lgkmcnt(0)
	v_mfma_f32_16x16x32_bf16 v[66:69], v[144:147], v[188:191], v[66:69]
	v_mfma_f32_16x16x32_bf16 v[62:65], v[164:167], v[188:191], v[62:65]
	v_mfma_f32_16x16x32_bf16 v[50:53], v[144:147], v[218:221], v[50:53]
	v_mfma_f32_16x16x32_bf16 v[46:49], v[164:167], v[218:221], v[46:49]
	v_mfma_f32_16x16x32_bf16 v[34:37], v[144:147], v[226:229], v[34:37]
	v_mfma_f32_16x16x32_bf16 v[30:33], v[164:167], v[226:229], v[30:33]
	v_mfma_f32_16x16x32_bf16 v[18:21], v[144:147], v[234:237], v[18:21]
	v_mfma_f32_16x16x32_bf16 v[14:17], v[164:167], v[234:237], v[14:17]
	v_mfma_f32_16x16x32_bf16 v[66:69], v[160:163], v[214:217], v[66:69]
	v_mfma_f32_16x16x32_bf16 v[62:65], v[168:171], v[214:217], v[62:65]
	v_mfma_f32_16x16x32_bf16 v[50:53], v[160:163], v[222:225], v[50:53]
	v_mfma_f32_16x16x32_bf16 v[46:49], v[168:171], v[222:225], v[46:49]
	v_mfma_f32_16x16x32_bf16 v[34:37], v[160:163], v[230:233], v[34:37]
	v_mfma_f32_16x16x32_bf16 v[30:33], v[168:171], v[230:233], v[30:33]
	v_mfma_f32_16x16x32_bf16 v[18:21], v[160:163], v[238:241], v[18:21]
	v_mfma_f32_16x16x32_bf16 v[14:17], v[168:171], v[238:241], v[14:17]
	s_nop 0
	s_nop 0
	v_mfma_f32_16x16x32_bf16 v[58:61], v[172:175], v[188:191], v[58:61]
	v_mfma_f32_16x16x32_bf16 v[54:57], v[180:183], v[188:191], v[54:57]
	v_mfma_f32_16x16x32_bf16 v[42:45], v[172:175], v[218:221], v[42:45]
	v_mfma_f32_16x16x32_bf16 v[38:41], v[180:183], v[218:221], v[38:41]
	v_mfma_f32_16x16x32_bf16 v[26:29], v[172:175], v[226:229], v[26:29]
	v_mfma_f32_16x16x32_bf16 v[22:25], v[180:183], v[226:229], v[22:25]
	v_mfma_f32_16x16x32_bf16 v[6:9], v[172:175], v[234:237], v[6:9]
	v_mfma_f32_16x16x32_bf16 v[2:5], v[180:183], v[234:237], v[2:5]
	v_mfma_f32_16x16x32_bf16 v[58:61], v[176:179], v[214:217], v[58:61]
	v_mfma_f32_16x16x32_bf16 v[54:57], v[184:187], v[214:217], v[54:57]
	v_mfma_f32_16x16x32_bf16 v[42:45], v[176:179], v[222:225], v[42:45]
	v_mfma_f32_16x16x32_bf16 v[38:41], v[184:187], v[222:225], v[38:41]
	v_mfma_f32_16x16x32_bf16 v[26:29], v[176:179], v[230:233], v[26:29]
	v_mfma_f32_16x16x32_bf16 v[22:25], v[184:187], v[230:233], v[22:25]
	v_mfma_f32_16x16x32_bf16 v[6:9], v[176:179], v[238:241], v[6:9]
	v_mfma_f32_16x16x32_bf16 v[2:5], v[184:187], v[238:241], v[2:5]
	s_nop 0
	s_barrier
	s_add_i32 s49, s49, 2
	s_add_u32 s39, s39, 0x100
	s_addc_u32 s47, s47, 0
	s_add_u32 s56, s56, 0x100
	s_addc_u32 s57, s57, 0
	s_cmp_gt_u32 s49, 13
	s_cbranch_scc0 .LBB0_294
	s_and_b64 vcc, exec, s[44:45]
	s_cbranch_vccz .LBB0_297
	s_barrier

; __device__ __forceinline__ unsigned cvt_pk_bf16(float lo, float hi) { unsigned r; asm volatile("v_cvt_pk_bf16_f32 %0, %1, %2" : "=v"(r) : "v"(lo), "v"(hi)); return r; }
; __global__ void __launch_bounds__(512, 2) fwd_kernel(KArgs a) {
;     ...
;             if (l == 0 && hf == 0) for (int r_ = 0; r_ < REP_EXP; ++r_) {
;                 IDS;
;                 for (int t = gt; t < 2 * 16 * 256 * 64; t += NGT) {
;                     const int kc = t & 63, n = (t >> 6) & 255, g = (t >> 14) & 15, ll = t >> 18;
;                     const int d = n >> 7, ri = (n >> 6) & 1, p = n & 63, k0 = kc * 8, sp = k0 >> 4, j0 = k0 & 15, e = d == 0 ? 31 - sp : sp;
;                     const float* pw = POW + ((size_t)(((ll * 2 + d) * 16 + g) * 33 + e) * 64 + p) * 2; const float pr = pw[0], pi = pw[1];
;                     const float* bb = BBAR + (((size_t)((ll * 2 + d) * 16 + g) * 64 + p) * 16 + j0) * 2; float v[8];
; #pragma unroll
;                     for (int j = 0; j < 8; ++j) { const float br = bb[2 * j], bi = bb[2 * j + 1]; v[j] = ri == 0 ? pr * br - pi * bi : pr * bi + pi * br; }
;                     u32x4 o; o.x = cvt_pk_bf16(v[0], v[1]); o.y = cvt_pk_bf16(v[2], v[3]); o.z = cvt_pk_bf16(v[4], v[5]); o.w = cvt_pk_bf16(v[6], v[7]);
;                     *(u32x4*)(WEND + ((size_t)(ll * 16 + g) * 256 + n) * 512 + k0) = o;
;                 }
.LBB0_365:
	s_setprio 0
	v_readlane_b32 s36, v254, 14
	v_readlane_b32 s20, v250, 23
	s_cmp_lg_u32 s36, 0
	s_cbranch_scc1 .Lmy_exp_skip
	s_lshl_b32 s21, s20, 18
	s_add_i32 s78, s21, 0x40000
	s_mul_i32 s79, s20, 0xc0000
	s_add_i32 s1, s79, 0xc0000
	s_cmp_lt_u32 s91, 8
	s_cbranch_scc1 .Lmy_exp_skip
	s_sub_i32 s64, s91, 8
	s_sub_i32 s65, s74, 8
	s_lshl_b32 s44, s64, 9
	s_lshl_b32 s46, s65, 9
	v_readlane_b32 s22, v251, 30
	v_readlane_b32 s23, v251, 31
	v_readlane_b32 s24, v251, 32
	v_readlane_b32 s25, v251, 33
	s_mov_b64 s[36:37], s[72:73]
	v_mov_b32_e32 v61, v194
	s_mov_b32 s38, s78
	v_add_u32_e32 v60, s44, v61
	v_add_u32_e32 v60, s21, v60
	v_cmp_gt_i32_e32 vcc, s38, v60
	s_and_saveexec_b64 s[38:39], vcc
	s_cbranch_execz .Lmy_exp_146
	s_add_u32 s40, s36, 0x2330000
	s_addc_u32 s41, s37, 0
	s_add_u32 s42, s36, 0x2438000
	s_addc_u32 s43, s37, 0
	s_add_u32 s52, s36, 0x26b8000
	v_lshlrev_b32_e32 v61, 3, v61
	s_addc_u32 s53, s37, 0
	v_lshl_add_u32 v61, s64, 12, v61
	s_lshl_b32 s45, s65, 12
	s_mov_b64 s[54:55], 0
	s_movk_i32 s48, 0x80
	v_mov_b32_e32 v63, 0
	s_add_i32 s56, s78, -1
	v_mov_b32_e32 v64, v60
